# attention: running max folded into QK^T MFMA accumulator init (C=-m), per-tile subtractions removed; rescale only on >8 growth
# speedup vs baseline: 1.0971x; 1.0006x over previous
.LBB0_881:
	s_ashr_i32 s0, s16, 8
	s_add_i32 s6, s0, s10
	s_ashr_i32 s7, s16, 5
	s_and_b64 s[0:1], s[2:3], exec
	s_cselect_b32 s14, s6, s7
	s_and_b32 s6, s16, 31
	s_and_b64 s[0:1], s[2:3], exec
	s_cselect_b32 s0, s11, s6
	s_ashr_i32 s15, s14, 1
	s_and_b32 s17, s14, 1
	s_mul_i32 s18, s15, 0x90000
	s_mul_hi_i32 s1, s15, 0x90000
	s_add_u32 s6, s4, s18
	s_addc_u32 s7, s8, s1
	s_lshl_b32 s19, s17, 7
	s_add_u32 s6, s6, s19
	s_addc_u32 s7, s7, 0
	s_lshl_b32 s15, s15, 11
	s_lshl_b32 s0, s0, 6
	s_add_i32 s15, s15, s0
	v_add_u32_e32 v156, s15, v168
	v_ashrrev_i32_e32 v157, 31, v156
	v_readlane_b32 s20, v254, 21
	v_lshl_or_b32 v154, s17, 8, v135
	v_lshlrev_b64 v[2:3], 10, v[156:157]
	v_readlane_b32 s21, v254, 22
	v_lshlrev_b32_e32 v0, 1, v154
	v_lshl_add_u64 v[4:5], s[6:7], 0, v[140:141]
	v_lshl_add_u64 v[2:3], s[20:21], 0, v[2:3]
	v_mov_b32_e32 v151, v1
	v_lshl_add_u64 v[2:3], v[2:3], 0, v[0:1]
	v_mov_b32_e32 v149, v1
	v_lshl_add_u64 v[4:5], v[4:5], 0, v[150:151]
	v_lshl_add_u64 v[2:3], v[2:3], 0, v[148:149]
	v_mad_i64_i32 v[6:7], s[6:7], s14, v234, v[142:143]
	global_load_dwordx4 v[74:77], v[4:5], off
	global_load_dwordx4 v[90:93], v[6:7], off
	global_load_dwordx4 v[66:69], v[2:3], off
	global_load_dwordx4 v[70:73], v[2:3], off offset:32
	v_add_co_u32_e32 v4, vcc, s9, v4
	s_movk_i32 s0, 0x2400
	s_nop 0
	v_addc_co_u32_e32 v5, vcc, 0, v5, vcc
	global_load_dwordx4 v[86:89], v[4:5], off
	global_load_dwordx4 v[94:97], v[6:7], off offset:128
	global_load_dwordx4 v[78:81], v[2:3], off offset:64
	global_load_dwordx4 v[82:85], v[2:3], off offset:96
	v_mov_b32_e32 v2, v1
	v_mov_b32_e32 v3, v1
	v_mov_b32_e32 v4, v1
	v_mov_b32_e32 v5, v1
	v_mov_b32_e32 v6, v1
	v_mov_b32_e32 v7, v1
	v_mov_b32_e32 v8, v1
	v_mov_b32_e32 v9, v1
	v_mov_b32_e32 v10, v1
	v_mov_b32_e32 v11, v1
	v_mov_b32_e32 v12, v1
	v_mov_b32_e32 v13, v1
	v_mov_b32_e32 v14, v1
	v_mov_b32_e32 v15, v1
	v_mov_b32_e32 v16, v1
	v_mov_b32_e32 v17, v1
	v_mov_b32_e32 v18, v1
	v_mov_b32_e32 v19, v1
	v_mov_b32_e32 v20, v1
	v_mov_b32_e32 v21, v1
	v_mov_b32_e32 v22, v1
	v_mov_b32_e32 v23, v1
	v_mov_b32_e32 v24, v1
	v_mov_b32_e32 v25, v1
	v_mov_b32_e32 v26, v1
	v_mov_b32_e32 v27, v1
	v_mov_b32_e32 v28, v1
	v_mov_b32_e32 v29, v1
	v_mov_b32_e32 v30, v1
	v_mov_b32_e32 v31, v1
	v_add3_u32 v149, v169, v132, s0
	s_or_b32 s0, s18, s19
	v_mov_b32_e32 v0, v1
	v_mov_b64_e32 v[32:33], v[30:31]
	s_mov_b32 s17, 0
	v_mad_i64_i32 v[158:159], s[6:7], s14, v234, v[144:145]
	v_lshl_add_u64 v[160:161], v[146:147], 0, s[0:1]
	v_mov_b32_e32 v151, 0xf149f2ca
	s_mov_b32 s98, 0xff800000
	s_mov_b32 s99, 0xff800000
	v_mov_b32_e32 v206, 0
	v_mov_b32_e32 v207, 0
	v_mov_b32_e32 v208, 0
	v_mov_b32_e32 v209, 0
	v_mov_b32_e32 v210, 0
	v_mov_b32_e32 v211, 0
	v_mov_b32_e32 v212, 0
	v_mov_b32_e32 v213, 0
	v_mov_b32_e32 v214, 0
	v_mov_b32_e32 v215, 0
	v_mov_b32_e32 v216, 0
	v_mov_b32_e32 v217, 0
	v_mov_b32_e32 v218, 0
	v_mov_b32_e32 v219, 0
	v_mov_b32_e32 v220, 0
	v_mov_b32_e32 v221, 0
	v_mov_b32_e32 v153, 0
	v_mov_b64_e32 v[30:31], v[28:29]
	v_mov_b64_e32 v[28:29], v[26:27]
	v_mov_b64_e32 v[26:27], v[24:25]
	v_mov_b64_e32 v[24:25], v[22:23]
	v_mov_b64_e32 v[22:23], v[20:21]
	v_mov_b64_e32 v[20:21], v[18:19]
	v_mov_b64_e32 v[18:19], v[16:17]
	v_mov_b64_e32 v[16:17], v[14:15]
	v_mov_b64_e32 v[14:15], v[12:13]
	v_mov_b64_e32 v[12:13], v[10:11]
	v_mov_b64_e32 v[10:11], v[8:9]
	v_mov_b64_e32 v[8:9], v[6:7]
	v_mov_b64_e32 v[6:7], v[4:5]
	v_mov_b64_e32 v[4:5], v[2:3]
	v_mov_b64_e32 v[2:3], v[0:1]
	s_waitcnt lgkmcnt(0)
	s_barrier
	s_waitcnt vmcnt(7)
	ds_write_b128 v171, v[74:77]
	s_waitcnt vmcnt(6)
	ds_write2_b64 v149, v[90:91], v[92:93] offset1:1
	s_waitcnt lgkmcnt(0)
	s_barrier
	s_branch .LBB0_883

.LBB0_885:
	ds_read_b128 v[34:37], v172
	ds_read_b128 v[38:41], v172 offset:32
	ds_read_b128 v[42:45], v172 offset:64
	ds_read_b128 v[46:49], v172 offset:96
	ds_read_b128 v[98:101], v172 offset:4608
	ds_read_b128 v[102:105], v172 offset:4640
	ds_read_b128 v[106:109], v172 offset:4672
	ds_read_b128 v[110:113], v172 offset:4704
	s_waitcnt vmcnt(5) lgkmcnt(7)
	v_mfma_f32_32x32x16_bf16 v[50:65], v[34:37], v[66:69], v[206:221]
	v_add_u32_e32 v0, 0x2000, v173
	ds_read2_b64 v[126:129], v0 offset0:128 offset1:130
	ds_read2_b64 v[114:117], v0 offset0:132 offset1:134
	s_waitcnt vmcnt(4) lgkmcnt(8)
	v_mfma_f32_32x32x16_bf16 v[50:65], v[38:41], v[70:73], v[50:65]
	s_waitcnt vmcnt(1) lgkmcnt(7)
	v_mfma_f32_32x32x16_bf16 v[50:65], v[42:45], v[78:81], v[50:65]
	s_waitcnt vmcnt(0) lgkmcnt(6)
	v_mfma_f32_32x32x16_bf16 v[50:65], v[46:49], v[82:85], v[50:65]
	s_waitcnt lgkmcnt(5)
	v_mfma_f32_32x32x16_bf16 v[34:49], v[98:101], v[66:69], v[206:221]
	v_add_u32_e32 v98, 0x3000, v173
	s_waitcnt lgkmcnt(4)
	v_mfma_f32_32x32x16_bf16 v[34:49], v[102:105], v[70:73], v[34:49]
	s_waitcnt lgkmcnt(3)
	v_mfma_f32_32x32x16_bf16 v[34:49], v[106:109], v[78:81], v[34:49]
	s_waitcnt lgkmcnt(2)
	v_mfma_f32_32x32x16_bf16 v[34:49], v[110:113], v[82:85], v[34:49]
	ds_read2_b64 v[122:125], v98 offset0:160 offset1:162
	ds_read2_b64 v[118:121], v98 offset0:164 offset1:166
	ds_read2_b64 v[110:113], v0 offset0:136 offset1:138
	ds_read2_b64 v[106:109], v98 offset0:168 offset1:170
	ds_read2_b64 v[102:105], v0 offset0:140 offset1:142
	ds_read2_b64 v[98:101], v98 offset0:172 offset1:174
	v_max_f32_e32 v0, v51, v51
	v_max_f32_e32 v174, v50, v50
	v_max_f32_e32 v0, v174, v0
	v_max3_f32 v0, v0, v52, v53
	v_max3_f32 v0, v0, v54, v55
	v_max3_f32 v0, v0, v56, v57
	v_max3_f32 v0, v0, v58, v59
	v_max3_f32 v0, v0, v60, v61
	v_max3_f32 v0, v0, v62, v63
	v_max3_f32 v0, v0, v64, v65
	v_max3_f32 v0, v0, v34, v35
	v_max3_f32 v0, v0, v36, v37
	v_max3_f32 v0, v0, v38, v39
	v_max3_f32 v0, v0, v40, v41
	v_max3_f32 v0, v0, v42, v43
	v_max3_f32 v0, v0, v44, v45
	v_max3_f32 v0, v0, v46, v47
	v_max3_f32 v0, v0, v48, v49
	ds_bpermute_b32 v174, v170, v0
	s_waitcnt lgkmcnt(0)
	v_max_f32_e32 v174, v174, v174
	v_max_f32_e32 v0, v0, v174
	v_cmp_lt_f32_e32 vcc, s98, v0
	s_cbranch_vccz .LBB0_887
	v_max_f32_e32 v174, s99, v0
	v_sub_f32_e32 v0, 0, v174
	v_min_f32_e32 v0, 0, v0
	v_exp_f32_e32 v0, v0
	v_sub_f32_e32 v206, v206, v174
	v_add_f32_e32 v151, v151, v174
	v_mov_b32_e32 v207, v206
	v_mov_b32_e32 v208, v206
	v_mov_b32_e32 v209, v206
	v_mov_b32_e32 v210, v206
	v_mov_b32_e32 v211, v206
	v_mov_b32_e32 v212, v206
	v_mov_b32_e32 v213, v206
	v_mov_b32_e32 v214, v206
	v_mov_b32_e32 v215, v206
	v_mov_b32_e32 v216, v206
	v_mov_b32_e32 v217, v206
	v_mov_b32_e32 v218, v206
	v_mov_b32_e32 v219, v206
	v_mov_b32_e32 v220, v206
	v_mov_b32_e32 v221, v206
	v_mul_f32_e32 v153, v153, v0
	v_mul_f32_e32 v32, v32, v0
	v_mul_f32_e32 v33, v33, v0
	v_mul_f32_e32 v30, v30, v0
	v_mul_f32_e32 v31, v31, v0
	v_mul_f32_e32 v28, v28, v0
	v_mul_f32_e32 v29, v29, v0
	v_mul_f32_e32 v26, v26, v0
	v_mul_f32_e32 v27, v27, v0
	v_mul_f32_e32 v24, v24, v0
	v_mul_f32_e32 v25, v25, v0
	v_mul_f32_e32 v22, v22, v0
	v_mul_f32_e32 v23, v23, v0
	v_mul_f32_e32 v20, v20, v0
	v_mul_f32_e32 v21, v21, v0
	v_mul_f32_e32 v18, v18, v0
	v_mul_f32_e32 v19, v19, v0
	v_mul_f32_e32 v16, v16, v0
	v_mul_f32_e32 v17, v17, v0
	v_mul_f32_e32 v14, v14, v0
	v_mul_f32_e32 v15, v15, v0
	v_mul_f32_e32 v12, v12, v0
	v_mul_f32_e32 v13, v13, v0
	v_mul_f32_e32 v10, v10, v0
	v_mul_f32_e32 v11, v11, v0
	v_mul_f32_e32 v8, v8, v0
	v_mul_f32_e32 v9, v9, v0
	v_mul_f32_e32 v6, v6, v0
	v_mul_f32_e32 v7, v7, v0
	v_mul_f32_e32 v4, v4, v0
	v_mul_f32_e32 v5, v5, v0
	v_mul_f32_e32 v2, v2, v0
	v_mul_f32_e32 v3, v3, v0
	v_sub_f32_e32 v50, v50, v174
	v_sub_f32_e32 v51, v51, v174
	v_sub_f32_e32 v52, v52, v174
	v_sub_f32_e32 v53, v53, v174
	v_sub_f32_e32 v54, v54, v174
	v_sub_f32_e32 v55, v55, v174
	v_sub_f32_e32 v56, v56, v174
	v_sub_f32_e32 v57, v57, v174
	v_sub_f32_e32 v58, v58, v174
	v_sub_f32_e32 v59, v59, v174
	v_sub_f32_e32 v60, v60, v174
	v_sub_f32_e32 v61, v61, v174
	v_sub_f32_e32 v62, v62, v174
	v_sub_f32_e32 v63, v63, v174
	v_sub_f32_e32 v64, v64, v174
	v_sub_f32_e32 v65, v65, v174
	v_sub_f32_e32 v34, v34, v174
	v_sub_f32_e32 v35, v35, v174
	v_sub_f32_e32 v36, v36, v174
	v_sub_f32_e32 v37, v37, v174
	v_sub_f32_e32 v38, v38, v174
	v_sub_f32_e32 v39, v39, v174
	v_sub_f32_e32 v40, v40, v174
	v_sub_f32_e32 v41, v41, v174
	v_sub_f32_e32 v42, v42, v174
	v_sub_f32_e32 v43, v43, v174
	v_sub_f32_e32 v44, v44, v174
	v_sub_f32_e32 v45, v45, v174
	v_sub_f32_e32 v46, v46, v174
	v_sub_f32_e32 v47, v47, v174
	v_sub_f32_e32 v48, v48, v174
	v_sub_f32_e32 v49, v49, v174
	s_mov_b32 s98, 0x41000000
	s_mov_b32 s99, 0
.LBB0_887:
	v_exp_f32_e32 v0, v50
	v_exp_f32_e32 v50, v51
	v_exp_f32_e32 v51, v52
	v_exp_f32_e32 v52, v53
	v_exp_f32_e32 v53, v54
	v_exp_f32_e32 v54, v55
	v_exp_f32_e32 v55, v56
	v_exp_f32_e32 v56, v57
	v_exp_f32_e32 v57, v58
	v_exp_f32_e32 v58, v59
	v_exp_f32_e32 v59, v60
	v_exp_f32_e32 v60, v61
	v_exp_f32_e32 v61, v62
	v_exp_f32_e32 v62, v63
	v_exp_f32_e32 v63, v64
	v_exp_f32_e32 v64, v65
	v_exp_f32_e32 v34, v34
	v_exp_f32_e32 v35, v35
	v_exp_f32_e32 v36, v36
	v_exp_f32_e32 v37, v37
	v_exp_f32_e32 v38, v38
	v_exp_f32_e32 v39, v39
	v_exp_f32_e32 v40, v40
	v_exp_f32_e32 v41, v41
	v_exp_f32_e32 v42, v42
	v_exp_f32_e32 v43, v43
	v_exp_f32_e32 v44, v44
	v_exp_f32_e32 v45, v45
	v_exp_f32_e32 v46, v46
	v_exp_f32_e32 v47, v47
	v_exp_f32_e32 v48, v48
	v_exp_f32_e32 v49, v49
	v_cvt_pk_bf16_f32 v174, v0, v50
	v_cvt_pk_bf16_f32 v175, v51, v52
	v_cvt_pk_bf16_f32 v176, v53, v54
	v_cvt_pk_bf16_f32 v177, v55, v56
	v_cvt_pk_bf16_f32 v178, v57, v58
	v_cvt_pk_bf16_f32 v179, v59, v60
	v_cvt_pk_bf16_f32 v180, v61, v62
	v_cvt_pk_bf16_f32 v181, v63, v64
	v_cvt_pk_bf16_f32 v182, v34, v35
	v_cvt_pk_bf16_f32 v183, v36, v37
	v_cvt_pk_bf16_f32 v184, v38, v39
	v_cvt_pk_bf16_f32 v185, v40, v41
	v_cvt_pk_bf16_f32 v186, v42, v43
	v_cvt_pk_bf16_f32 v187, v44, v45
	v_cvt_pk_bf16_f32 v188, v46, v47
	v_cvt_pk_bf16_f32 v189, v48, v49
	v_mfma_f32_32x32x16_bf16 v[2:17], v[126:129], v[174:177], v[2:17]
	v_mfma_f32_32x32x16_bf16 v[18:33], v[122:125], v[174:177], v[18:33]
	v_mfma_f32_32x32x16_bf16 v[2:17], v[114:117], v[178:181], v[2:17]
	v_mfma_f32_32x32x16_bf16 v[18:33], v[118:121], v[178:181], v[18:33]
	v_mfma_f32_32x32x16_bf16 v[2:17], v[110:113], v[182:185], v[2:17]
	v_mfma_f32_32x32x16_bf16 v[18:33], v[106:109], v[182:185], v[18:33]
	v_mfma_f32_32x32x16_bf16 v[2:17], v[102:105], v[186:189], v[2:17]
	v_mfma_f32_32x32x16_bf16 v[18:33], v[98:101], v[186:189], v[18:33]
	s_movk_i32 s0, 0x6a00
	v_add3_u32 v65, v169, v132, s0
	s_cmp_gt_u32 s17, 32
	ds_write_b128 v171, v[86:89] offset:17920
	ds_write2_b64 v65, v[94:95], v[96:97] offset1:1
	s_waitcnt lgkmcnt(0)
	s_barrier
	s_cbranch_scc1 .LBB0_889
	v_add_co_u32_e32 v86, vcc, 0x1370c000, v164
	s_nop 1
	v_addc_co_u32_e32 v87, vcc, 0, v165, vcc
	v_add_co_u32_e32 v94, vcc, 0x14000000, v162
	global_load_dwordx4 v[86:89], v[86:87], off
	s_nop 0
	v_addc_co_u32_e32 v95, vcc, 0, v163, vcc
	global_load_dwordx4 v[94:97], v[94:95], off offset:384
.LBB0_889:
	v_add_f32_e32 v0, 0, v0
	v_add_f32_e32 v0, v50, v0
	v_add_f32_e32 v0, v51, v0
	v_add_f32_e32 v0, v52, v0
	v_add_f32_e32 v0, v53, v0
	v_add_f32_e32 v0, v54, v0
	v_add_f32_e32 v0, v55, v0
	v_add_f32_e32 v0, v56, v0
	v_add_f32_e32 v0, v57, v0
	v_add_f32_e32 v0, v58, v0
	v_add_f32_e32 v0, v59, v0
	v_add_f32_e32 v0, v60, v0
	v_add_f32_e32 v0, v61, v0
	v_add_f32_e32 v0, v62, v0
	v_add_f32_e32 v0, v63, v0
	v_add_f32_e32 v0, v64, v0
	v_add_f32_e32 v0, v34, v0
	v_add_f32_e32 v0, v35, v0
	v_add_f32_e32 v0, v36, v0
	v_add_f32_e32 v0, v37, v0
	v_add_f32_e32 v0, v38, v0
	v_add_f32_e32 v0, v39, v0
	v_add_f32_e32 v0, v40, v0
	v_add_f32_e32 v0, v41, v0
	v_add_f32_e32 v0, v42, v0
	v_add_f32_e32 v0, v43, v0
	v_add_f32_e32 v0, v44, v0
	v_add_f32_e32 v0, v45, v0
	v_add_f32_e32 v0, v46, v0
	v_add_f32_e32 v0, v47, v0
	v_add_f32_e32 v0, v48, v0
	v_add_f32_e32 v0, v49, v0
	ds_read_b128 v[34:37], v172 offset:17920
	ds_read_b128 v[38:41], v172 offset:17952
	ds_read_b128 v[42:45], v172 offset:17984
	ds_read_b128 v[46:49], v172 offset:18016
	ds_read_b128 v[98:101], v172 offset:22528
	ds_read_b128 v[102:105], v172 offset:22560
	ds_read_b128 v[106:109], v172 offset:22592
	ds_read_b128 v[110:113], v172 offset:22624
	v_add_f32_e32 v0, v153, v0
	s_waitcnt lgkmcnt(7)
	v_mfma_f32_32x32x16_bf16 v[50:65], v[34:37], v[66:69], v[206:221]
	s_waitcnt lgkmcnt(6)
	v_mfma_f32_32x32x16_bf16 v[50:65], v[38:41], v[70:73], v[50:65]
	s_waitcnt lgkmcnt(5)
	v_mfma_f32_32x32x16_bf16 v[50:65], v[42:45], v[78:81], v[50:65]
	s_waitcnt lgkmcnt(4)
	v_mfma_f32_32x32x16_bf16 v[50:65], v[46:49], v[82:85], v[50:65]
	s_waitcnt lgkmcnt(3)
	v_mfma_f32_32x32x16_bf16 v[34:49], v[98:101], v[66:69], v[206:221]
	v_add_u32_e32 v98, 0x6800, v173
	v_add_u32_e32 v99, 0x7800, v173
	ds_read2_b64 v[126:129], v98 offset0:64 offset1:66
	ds_read2_b64 v[114:117], v98 offset0:68 offset1:70
	s_waitcnt lgkmcnt(4)
	v_mfma_f32_32x32x16_bf16 v[34:49], v[102:105], v[70:73], v[34:49]
	s_waitcnt lgkmcnt(3)
	v_mfma_f32_32x32x16_bf16 v[34:49], v[106:109], v[78:81], v[34:49]
	s_waitcnt lgkmcnt(2)
	v_mfma_f32_32x32x16_bf16 v[34:49], v[110:113], v[82:85], v[34:49]
	ds_read2_b64 v[122:125], v99 offset0:96 offset1:98
	ds_read2_b64 v[118:121], v99 offset0:100 offset1:102
	ds_read2_b64 v[110:113], v98 offset0:72 offset1:74
	ds_read2_b64 v[106:109], v99 offset0:104 offset1:106
	ds_read2_b64 v[102:105], v98 offset0:76 offset1:78
	ds_read2_b64 v[98:101], v99 offset0:108 offset1:110
	v_max_f32_e32 v153, v51, v51
	v_max_f32_e32 v162, v50, v50
	v_max_f32_e32 v153, v162, v153
	v_max3_f32 v153, v153, v52, v53
	v_max3_f32 v153, v153, v54, v55
	v_max3_f32 v153, v153, v56, v57
	v_max3_f32 v153, v153, v58, v59
	v_max3_f32 v153, v153, v60, v61
	v_max3_f32 v153, v153, v62, v63
	v_max3_f32 v153, v153, v64, v65
	v_max3_f32 v153, v153, v34, v35
	v_max3_f32 v153, v153, v36, v37
	v_max3_f32 v153, v153, v38, v39
	v_max3_f32 v153, v153, v40, v41
	v_max3_f32 v153, v153, v42, v43
	v_max3_f32 v153, v153, v44, v45
	v_max3_f32 v153, v153, v46, v47
	v_max3_f32 v153, v153, v48, v49
	ds_bpermute_b32 v162, v170, v153
	s_waitcnt lgkmcnt(0)
	v_max_f32_e32 v162, v162, v162
	v_max_f32_e32 v153, v153, v162
	v_cmp_lt_f32_e32 vcc, s98, v153
	s_cbranch_vccz .LBB0_891
	v_max_f32_e32 v162, s99, v153
	v_sub_f32_e32 v153, 0, v162
	v_min_f32_e32 v153, 0, v153
	v_exp_f32_e32 v153, v153
	v_sub_f32_e32 v206, v206, v162
	v_add_f32_e32 v151, v151, v162
	v_mov_b32_e32 v207, v206
	v_mov_b32_e32 v208, v206
	v_mov_b32_e32 v209, v206
	v_mov_b32_e32 v210, v206
	v_mov_b32_e32 v211, v206
	v_mov_b32_e32 v212, v206
	v_mov_b32_e32 v213, v206
	v_mov_b32_e32 v214, v206
	v_mov_b32_e32 v215, v206
	v_mov_b32_e32 v216, v206
	v_mov_b32_e32 v217, v206
	v_mov_b32_e32 v218, v206
	v_mov_b32_e32 v219, v206
	v_mov_b32_e32 v220, v206
	v_mov_b32_e32 v221, v206
	v_mul_f32_e32 v0, v0, v153
	v_mul_f32_e32 v32, v32, v153
	v_mul_f32_e32 v33, v33, v153
	v_mul_f32_e32 v30, v30, v153
	v_mul_f32_e32 v31, v31, v153
	v_mul_f32_e32 v28, v28, v153
	v_mul_f32_e32 v29, v29, v153
	v_mul_f32_e32 v26, v26, v153
	v_mul_f32_e32 v27, v27, v153
	v_mul_f32_e32 v24, v24, v153
	v_mul_f32_e32 v25, v25, v153
	v_mul_f32_e32 v22, v22, v153
	v_mul_f32_e32 v23, v23, v153
	v_mul_f32_e32 v20, v20, v153
	v_mul_f32_e32 v21, v21, v153
	v_mul_f32_e32 v18, v18, v153
	v_mul_f32_e32 v19, v19, v153
	v_mul_f32_e32 v16, v16, v153
	v_mul_f32_e32 v17, v17, v153
	v_mul_f32_e32 v14, v14, v153
	v_mul_f32_e32 v15, v15, v153
	v_mul_f32_e32 v12, v12, v153
	v_mul_f32_e32 v13, v13, v153
	v_mul_f32_e32 v10, v10, v153
	v_mul_f32_e32 v11, v11, v153
	v_mul_f32_e32 v8, v8, v153
	v_mul_f32_e32 v9, v9, v153
	v_mul_f32_e32 v6, v6, v153
	v_mul_f32_e32 v7, v7, v153
	v_mul_f32_e32 v4, v4, v153
	v_mul_f32_e32 v5, v5, v153
	v_mul_f32_e32 v2, v2, v153
	v_mul_f32_e32 v3, v3, v153
	v_sub_f32_e32 v50, v50, v162
	v_sub_f32_e32 v51, v51, v162
	v_sub_f32_e32 v52, v52, v162
	v_sub_f32_e32 v53, v53, v162
	v_sub_f32_e32 v54, v54, v162
	v_sub_f32_e32 v55, v55, v162
	v_sub_f32_e32 v56, v56, v162
	v_sub_f32_e32 v57, v57, v162
	v_sub_f32_e32 v58, v58, v162
	v_sub_f32_e32 v59, v59, v162
	v_sub_f32_e32 v60, v60, v162
	v_sub_f32_e32 v61, v61, v162
	v_sub_f32_e32 v62, v62, v162
	v_sub_f32_e32 v63, v63, v162
	v_sub_f32_e32 v64, v64, v162
	v_sub_f32_e32 v65, v65, v162
	v_sub_f32_e32 v34, v34, v162
	v_sub_f32_e32 v35, v35, v162
	v_sub_f32_e32 v36, v36, v162
	v_sub_f32_e32 v37, v37, v162
	v_sub_f32_e32 v38, v38, v162
	v_sub_f32_e32 v39, v39, v162
	v_sub_f32_e32 v40, v40, v162
	v_sub_f32_e32 v41, v41, v162
	v_sub_f32_e32 v42, v42, v162
	v_sub_f32_e32 v43, v43, v162
	v_sub_f32_e32 v44, v44, v162
	v_sub_f32_e32 v45, v45, v162
	v_sub_f32_e32 v46, v46, v162
	v_sub_f32_e32 v47, v47, v162
	v_sub_f32_e32 v48, v48, v162
	v_sub_f32_e32 v49, v49, v162
	s_mov_b32 s98, 0x41000000
	s_mov_b32 s99, 0
.LBB0_891:
	v_exp_f32_e32 v50, v50
	v_exp_f32_e32 v51, v51
	v_exp_f32_e32 v52, v52
	v_exp_f32_e32 v53, v53
	v_exp_f32_e32 v54, v54
	v_exp_f32_e32 v55, v55
	v_exp_f32_e32 v56, v56
	v_exp_f32_e32 v57, v57
	v_exp_f32_e32 v58, v58
	v_exp_f32_e32 v59, v59
	v_exp_f32_e32 v60, v60
	v_exp_f32_e32 v61, v61
	v_exp_f32_e32 v62, v62
	v_exp_f32_e32 v63, v63
	v_exp_f32_e32 v64, v64
	v_exp_f32_e32 v65, v65
	v_exp_f32_e32 v34, v34
	v_exp_f32_e32 v35, v35
	v_exp_f32_e32 v36, v36
	v_exp_f32_e32 v37, v37
	v_exp_f32_e32 v38, v38
	v_exp_f32_e32 v39, v39
	v_exp_f32_e32 v40, v40
	v_exp_f32_e32 v41, v41
	v_exp_f32_e32 v42, v42
	v_exp_f32_e32 v43, v43
	v_exp_f32_e32 v44, v44
	v_exp_f32_e32 v45, v45
	v_exp_f32_e32 v46, v46
	v_exp_f32_e32 v47, v47
	v_exp_f32_e32 v48, v48
	v_exp_f32_e32 v49, v49
	v_cvt_pk_bf16_f32 v162, v50, v51
	v_cvt_pk_bf16_f32 v163, v52, v53
	v_cvt_pk_bf16_f32 v164, v54, v55
	v_cvt_pk_bf16_f32 v165, v56, v57
	v_cvt_pk_bf16_f32 v174, v58, v59
	v_cvt_pk_bf16_f32 v175, v60, v61
	v_cvt_pk_bf16_f32 v176, v62, v63
	v_cvt_pk_bf16_f32 v177, v64, v65
	v_cvt_pk_bf16_f32 v178, v34, v35
	v_cvt_pk_bf16_f32 v179, v36, v37
	v_cvt_pk_bf16_f32 v180, v38, v39
	v_cvt_pk_bf16_f32 v181, v40, v41
	v_cvt_pk_bf16_f32 v182, v42, v43
	v_cvt_pk_bf16_f32 v183, v44, v45
	v_cvt_pk_bf16_f32 v184, v46, v47
	v_cvt_pk_bf16_f32 v185, v48, v49
	v_mfma_f32_32x32x16_bf16 v[2:17], v[126:129], v[162:165], v[2:17]
	v_mfma_f32_32x32x16_bf16 v[18:33], v[122:125], v[162:165], v[18:33]
	v_mfma_f32_32x32x16_bf16 v[2:17], v[114:117], v[174:177], v[2:17]
	v_mfma_f32_32x32x16_bf16 v[18:33], v[118:121], v[174:177], v[18:33]
	v_mfma_f32_32x32x16_bf16 v[2:17], v[110:113], v[178:181], v[2:17]
	v_mfma_f32_32x32x16_bf16 v[18:33], v[106:109], v[178:181], v[18:33]
	v_mfma_f32_32x32x16_bf16 v[2:17], v[102:105], v[182:185], v[2:17]
	v_mfma_f32_32x32x16_bf16 v[18:33], v[98:101], v[182:185], v[18:33]
	s_andn2_b64 vcc, exec, s[14:15]
	s_cbranch_vccnz .LBB0_882
	ds_write_b128 v171, v[74:77]
	ds_write2_b64 v149, v[90:91], v[92:93] offset1:1
	s_branch .LBB0_882
